# attention: K/V tile LDS writes hoisted mid-body (off the barrier critical path), group-0 softmax VALU ahead of first QK MFMA
# speedup vs baseline: 1.0327x; 1.0105x over previous
; template <int MODE>
; __device__ __forceinline__ void attn_phase(const Args& a, bool do_ctx, LAS unsigned char* lds, const int wid_s) {
;     ...
;         const unsigned skn = (unsigned)((tid >> 3) * KROW + (tid & 7) * 16);
;         const unsigned skr = (unsigned)(((tid & 255) >> 2) * KROW + 128 + (tid & 3) * 16);
;         const unsigned svt = (unsigned)((tid >> 3) * VROW + (tid & 7) * 16);
.LBB0_420:
	s_barrier
	v_mbcnt_lo_u32_b32 v1, -1, 0
	v_mbcnt_hi_u32_b32 v1, -1, v1
	v_readlane_b32 s0, v249, 8
	v_and_b32_e32 v5, 31, v1
	v_readlane_b32 s2, v249, 38
	v_add_u32_e32 v3, s0, v1
	v_and_b32_e32 v4, 63, v1
	v_bfe_u32 v6, v1, 5, 1
	v_or_b32_e32 v158, s2, v5
	v_and_b32_e32 v7, 7, v1
	v_lshlrev_b32_e32 v1, 4, v1
	v_readlane_b32 s2, v249, 50
	v_and_b32_e32 v132, 48, v1
	v_mov_b32_e32 v133, v201
	v_readlane_b32 s3, v249, 51
	v_readlane_b32 s0, v250, 5
	v_lshlrev_b32_e32 v136, 4, v7
	v_lshl_add_u64 v[134:135], s[2:3], 0, v[132:133]
	v_readlane_b32 s2, v249, 58
	v_mov_b32_e32 v137, v201
	v_readlane_b32 s3, v249, 59
	v_readlane_b32 s1, v250, 6
	v_ashrrev_i32_e32 v159, 3, v3
	v_lshl_add_u64 v[138:139], s[2:3], 0, v[136:137]
	s_movk_i32 s3, 0xd0
	s_movk_i32 s2, 0xffb8
	s_and_b64 s[0:1], s[0:1], exec
	v_lshlrev_b32_e32 v0, 3, v6
	v_bfe_u32 v160, v3, 2, 6
	v_mul_lo_u32 v1, v159, s3
	v_mul_lo_u32 v161, v159, s2
	s_movk_i32 s2, 0x100
	v_lshlrev_b32_e32 v4, 2, v4
	s_movk_i32 s0, 0x420
	s_mov_b32 s1, 0
	v_lshlrev_b32_e32 v2, 3, v7
	v_add3_u32 v162, v1, v136, 0
	v_cmp_gt_i32_e64 s[6:7], s2, v3
	v_mad_u32_u24 v1, v160, s3, v132
	v_mad_u32_u24 v3, v5, s3, 0
	v_lshlrev_b32_e32 v7, 4, v6
	v_xor_b32_e32 v163, 0x80, v4
	v_add_u32_e32 v8, 0, v0
	v_mul_u32_u24_e32 v5, 0x88, v5
	v_lshlrev_b32_e32 v4, 2, v6
	s_cselect_b32 s0, s0, 0x400
	v_lshlrev_b32_e32 v200, 1, v0
	v_lshlrev_b32_e32 v140, 1, v2
	v_lshlrev_b32_e32 v142, 1, v4
	v_add_u32_e32 v164, 0, v1
	v_add_u32_e32 v165, v3, v7
	v_add_u32_e32 v166, v8, v5
	v_add_u32_e32 v240, 0x6800, v166
	v_add_u32_e32 v241, 0x7800, v166
	v_add_u32_e32 v242, 0x8800, v166
	v_add_u32_e32 v243, 0x9800, v166
	s_mov_b32 s2, 0x8a00
	v_add3_u32 v251, v162, v161, s2
	s_mov_b32 s24, s1
	s_branch .LBB0_423

; #define LAS __attribute__((address_space(3)))
; __device__ __forceinline__ unsigned pk_bf16(float lo, float hi) { unsigned r; asm("v_cvt_pk_bf16_f32 %0, %1, %2" : "=v"(r) : "v"(lo), "v"(hi)); return r; }
; __device__ __forceinline__ float fexp2(float x) { return __builtin_amdgcn_exp2f(x); }
; #define ATT_WRITEK(rk, rr, buf) do { LAS unsigned char* nb_ = lds + (buf) * KBUF; *(LAS u32x4*)(nb_ + skn) = rk; if (tid < 256) *(LAS u32x4*)(nb_ + skr) = rr; } while (0)
; #define ATT_WRITEV(rv, buf) do { LAS u32x2* p_ = (LAS u32x2*)(ldsv + (buf) * VBUF + svt); u32x2 lo_ = {rv[0], rv[1]}, hi_ = {rv[2], rv[3]}; p_[0] = lo_; p_[1] = hi_; } while (0)
; template <int MODE>
; __device__ __forceinline__ void attn_pv(const LAS unsigned char* vb_, f32x16 (&st)[2], f32x16 (&ot)[2], float& mrun, float& lsum, const int ql, const int hf, const int lane) {
;     ...
;     float ps = 0.f;
; #pragma unroll
;     for (int kb = 0; kb < 2; ++kb)
; #pragma unroll
;         for (int i = 0; i < 16; ++i) { const float p = fexp2(st[kb][i] - mrun); st[kb][i] = p; ps += p; }
;     lsum += ps;
;     } else lsum += st[0][0];
; #pragma unroll
;     for (int kb = 0; kb < 2; ++kb)
; #pragma unroll
;         for (int sI = 0; sI < 2; ++sI) {
;             u32x4 pw = {pk_bf16(st[kb][8 * sI + 0], st[kb][8 * sI + 1]), pk_bf16(st[kb][8 * sI + 2], st[kb][8 * sI + 3]),
;                         pk_bf16(st[kb][8 * sI + 4], st[kb][8 * sI + 5]), pk_bf16(st[kb][8 * sI + 6], st[kb][8 * sI + 7])};
;             const bf16x8 pf = __builtin_bit_cast(bf16x8, pw);
; #pragma unroll
;             for (int db = 0; db < 2; ++db) {
;                 const LAS unsigned char* vp = vb_ + (db * 32 + ql) * VROW + (kb * 32 + 16 * sI + 4 * hf) * 2;
;                 const u32x2 v0 = *(const LAS u32x2*)vp, v1 = *(const LAS u32x2*)(vp + 16);
;                 u32x4 vw = {v0[0], v0[1], v1[0], v1[1]};
;                 ot[db] = att_mma<MODE>(__builtin_bit_cast(bf16x8, vw), pf, ot[db]);
;             }
;         }
; }
; template <int MODE>
; __device__ __forceinline__ void attn_phase(const Args& a, bool do_ctx, LAS unsigned char* lds, const int wid_s) {
;     ...
;             if (t + 2 < nkt) ATT_WRITEK(kK, kR, 0);
;             ATT_WRITEV(vV, 1);
.Latt_e_nors:
	s_cmp_lg_u32 s90, 0
	s_cbranch_scc1 .Latt_e_nors_fast
	v_sub_f32_e32 v48, v48, v143
	v_sub_f32_e32 v49, v49, v143
	v_sub_f32_e32 v50, v50, v143
	v_sub_f32_e32 v51, v51, v143
	v_sub_f32_e32 v52, v52, v143
	v_sub_f32_e32 v53, v53, v143
	v_sub_f32_e32 v54, v54, v143
	v_sub_f32_e32 v55, v55, v143
	v_exp_f32_e32 v48, v48
	v_exp_f32_e32 v49, v49
	v_exp_f32_e32 v50, v50
	v_exp_f32_e32 v51, v51
	v_exp_f32_e32 v52, v52
	v_exp_f32_e32 v53, v53
	v_exp_f32_e32 v54, v54
	v_exp_f32_e32 v55, v55
	s_waitcnt lgkmcnt(14)
	v_mfma_f32_32x32x16_bf16 v[80:95], v[64:67], v[112:115], 0
	v_cvt_pk_bf16_f32 v152, v48, v49
	v_cvt_pk_bf16_f32 v153, v50, v51
	v_cvt_pk_bf16_f32 v154, v52, v53
	v_cvt_pk_bf16_f32 v155, v54, v55
	s_waitcnt lgkmcnt(12)
	v_mfma_f32_32x32x16_bf16 v[64:79], v[68:71], v[112:115], 0
	v_add_f32_e32 v230, 0, v48
	v_add_f32_e32 v230, v49, v230
	v_add_f32_e32 v230, v50, v230
	v_add_f32_e32 v230, v51, v230
	v_add_f32_e32 v230, v52, v230
	v_add_f32_e32 v230, v53, v230
	v_add_f32_e32 v230, v54, v230
	v_add_f32_e32 v230, v55, v230
	v_mfma_f32_32x32x16_bf16 v[80:95], v[168:171], v[96:99], v[80:95]
	v_sub_f32_e32 v56, v56, v143
	v_sub_f32_e32 v57, v57, v143
	v_sub_f32_e32 v58, v58, v143
	v_sub_f32_e32 v59, v59, v143
	v_sub_f32_e32 v60, v60, v143
	v_sub_f32_e32 v61, v61, v143
	v_sub_f32_e32 v62, v62, v143
	v_sub_f32_e32 v63, v63, v143
	s_waitcnt lgkmcnt(11)
	v_mfma_f32_32x32x16_bf16 v[64:79], v[172:175], v[96:99], v[64:79]
	ds_read_b128 v[168:171], v165 offset:13440
	ds_read_b128 v[172:175], v165 offset:13472
	ds_read_b128 v[192:195], v165 offset:20096
	ds_read_b128 v[196:199], v165 offset:20128
	v_exp_f32_e32 v56, v56
	v_exp_f32_e32 v57, v57
	v_exp_f32_e32 v58, v58
	v_exp_f32_e32 v59, v59
	s_waitcnt lgkmcnt(14)
	v_mfma_f32_32x32x16_bf16 v[80:95], v[176:179], v[100:103], v[80:95]
	ds_read2_b64 a[0:3], v241 offset0:44 offset1:46
	v_exp_f32_e32 v60, v60
	v_exp_f32_e32 v61, v61
	v_exp_f32_e32 v62, v62
	v_exp_f32_e32 v63, v63
	s_waitcnt lgkmcnt(13)
	v_mfma_f32_32x32x16_bf16 v[64:79], v[184:187], v[100:103], v[64:79]
	v_mfma_f32_32x32x16_bf16 v[80:95], v[180:183], v[104:107], v[80:95]
	v_cvt_pk_bf16_f32 v48, v56, v57
	v_cvt_pk_bf16_f32 v49, v58, v59
	v_cvt_pk_bf16_f32 v50, v60, v61
	v_cvt_pk_bf16_f32 v51, v62, v63
	s_waitcnt lgkmcnt(12)
	v_mfma_f32_32x32x16_bf16 v[64:79], v[188:191], v[104:107], v[64:79]
	s_waitcnt lgkmcnt(10)
	v_mfma_f32_32x32x16_bf16 v[16:31], v[206:209], v[152:155], v[16:31]
	v_add_f32_e32 v230, v56, v230
	v_add_f32_e32 v230, v57, v230
	v_add_f32_e32 v230, v58, v230
	v_add_f32_e32 v230, v59, v230
	v_add_f32_e32 v230, v60, v230
	v_add_f32_e32 v230, v61, v230
	v_add_f32_e32 v230, v62, v230
	v_add_f32_e32 v230, v63, v230
	v_mfma_f32_32x32x16_bf16 v[0:15], v[210:213], v[152:155], v[0:15]
	v_sub_f32_e32 v32, v32, v143
	v_sub_f32_e32 v33, v33, v143
	v_sub_f32_e32 v34, v34, v143
	v_sub_f32_e32 v35, v35, v143
	v_sub_f32_e32 v36, v36, v143
	v_sub_f32_e32 v37, v37, v143
	v_sub_f32_e32 v38, v38, v143
	v_sub_f32_e32 v39, v39, v143
	s_waitcnt lgkmcnt(4)
	v_mfma_f32_32x32x16_bf16 v[80:95], v[168:171], v[108:111], v[80:95]
	v_exp_f32_e32 v32, v32
	v_exp_f32_e32 v33, v33
	v_exp_f32_e32 v34, v34
	v_exp_f32_e32 v35, v35
	v_mfma_f32_32x32x16_bf16 v[16:31], v[214:217], v[48:51], v[16:31]
	v_exp_f32_e32 v36, v36
	v_exp_f32_e32 v37, v37
	v_exp_f32_e32 v38, v38
	v_exp_f32_e32 v39, v39
	v_mfma_f32_32x32x16_bf16 v[0:15], v[218:221], v[48:51], v[0:15]
	v_cvt_pk_bf16_f32 v152, v32, v33
	v_cvt_pk_bf16_f32 v153, v34, v35
	v_cvt_pk_bf16_f32 v154, v36, v37
	v_cvt_pk_bf16_f32 v155, v38, v39
	s_waitcnt lgkmcnt(2)
	v_mfma_f32_32x32x16_bf16 v[64:79], v[192:195], v[108:111], v[64:79]
	v_add_f32_e32 v230, v32, v230
	v_add_f32_e32 v230, v33, v230
	v_add_f32_e32 v230, v34, v230
	v_add_f32_e32 v230, v35, v230
	v_add_f32_e32 v230, v36, v230
	v_add_f32_e32 v230, v37, v230
	v_add_f32_e32 v230, v38, v230
	v_add_f32_e32 v230, v39, v230
	v_mfma_f32_32x32x16_bf16 v[80:95], v[172:175], v[116:119], v[80:95]
	v_sub_f32_e32 v40, v40, v143
	v_sub_f32_e32 v41, v41, v143
	v_sub_f32_e32 v42, v42, v143
	v_sub_f32_e32 v43, v43, v143
	v_sub_f32_e32 v44, v44, v143
	v_sub_f32_e32 v45, v45, v143
	v_sub_f32_e32 v46, v46, v143
	v_sub_f32_e32 v47, v47, v143
	s_waitcnt lgkmcnt(1)
	v_mfma_f32_32x32x16_bf16 v[64:79], v[196:199], v[116:119], v[64:79]
	s_andn2_b64 vcc, exec, s[10:11]
	s_cbranch_vccnz .Latt_wskip_e1
	s_waitcnt vmcnt(2)
	ds_write_b128 v162, v[120:123]
	s_and_saveexec_b64 s[2:3], s[6:7]
	s_cbranch_execz .Latt_wk_e1
	s_waitcnt vmcnt(1)
	ds_write_b128 v164, v[124:127] offset:128

; #define LAS __attribute__((address_space(3)))
; __device__ __forceinline__ unsigned pk_bf16(float lo, float hi) { unsigned r; asm("v_cvt_pk_bf16_f32 %0, %1, %2" : "=v"(r) : "v"(lo), "v"(hi)); return r; }
; __device__ __forceinline__ float fexp2(float x) { return __builtin_amdgcn_exp2f(x); }
; #define ATT_WRITEK(rk, rr, buf) do { LAS unsigned char* nb_ = lds + (buf) * KBUF; *(LAS u32x4*)(nb_ + skn) = rk; if (tid < 256) *(LAS u32x4*)(nb_ + skr) = rr; } while (0)
; #define ATT_WRITEV(rv, buf) do { LAS u32x2* p_ = (LAS u32x2*)(ldsv + (buf) * VBUF + svt); u32x2 lo_ = {rv[0], rv[1]}, hi_ = {rv[2], rv[3]}; p_[0] = lo_; p_[1] = hi_; } while (0)
; template <int MODE>
; __device__ __forceinline__ void attn_pv(const LAS unsigned char* vb_, f32x16 (&st)[2], f32x16 (&ot)[2], float& mrun, float& lsum, const int ql, const int hf, const int lane) {
;     ...
;     float ps = 0.f;
; #pragma unroll
;     for (int kb = 0; kb < 2; ++kb)
; #pragma unroll
;         for (int i = 0; i < 16; ++i) { const float p = fexp2(st[kb][i] - mrun); st[kb][i] = p; ps += p; }
;     lsum += ps;
;     } else lsum += st[0][0];
; #pragma unroll
;     for (int kb = 0; kb < 2; ++kb)
; #pragma unroll
;         for (int sI = 0; sI < 2; ++sI) {
;             u32x4 pw = {pk_bf16(st[kb][8 * sI + 0], st[kb][8 * sI + 1]), pk_bf16(st[kb][8 * sI + 2], st[kb][8 * sI + 3]),
;                         pk_bf16(st[kb][8 * sI + 4], st[kb][8 * sI + 5]), pk_bf16(st[kb][8 * sI + 6], st[kb][8 * sI + 7])};
;             const bf16x8 pf = __builtin_bit_cast(bf16x8, pw);
; #pragma unroll
;             for (int db = 0; db < 2; ++db) {
;                 const LAS unsigned char* vp = vb_ + (db * 32 + ql) * VROW + (kb * 32 + 16 * sI + 4 * hf) * 2;
;                 const u32x2 v0 = *(const LAS u32x2*)vp, v1 = *(const LAS u32x2*)(vp + 16);
;                 u32x4 vw = {v0[0], v0[1], v1[0], v1[1]};
;                 ot[db] = att_mma<MODE>(__builtin_bit_cast(bf16x8, vw), pf, ot[db]);
;             }
;         }
; }
; template <int MODE>
; __device__ __forceinline__ void attn_phase(const Args& a, bool do_ctx, LAS unsigned char* lds, const int wid_s) {
;     ...
;             if (t + 2 < nkt) ATT_WRITEK(kK, kR, 0);
;             ATT_WRITEV(vV, 1);
.Latt_wskip_e1:
	s_waitcnt vmcnt(0)
	ds_write2_b64 v251, v[128:129], v[130:131] offset1:1
	v_exp_f32_e32 v40, v40
	v_exp_f32_e32 v41, v41
	v_exp_f32_e32 v42, v42
	v_exp_f32_e32 v43, v43
	v_mfma_f32_32x32x16_bf16 v[16:31], v[222:225], v[152:155], v[16:31]
	v_exp_f32_e32 v44, v44
	v_exp_f32_e32 v45, v45
	v_exp_f32_e32 v46, v46
	v_exp_f32_e32 v47, v47
	v_mfma_f32_32x32x16_bf16 v[0:15], v[226:229], v[152:155], v[0:15]
	v_cvt_pk_bf16_f32 v48, v40, v41
	v_cvt_pk_bf16_f32 v49, v42, v43
	v_cvt_pk_bf16_f32 v50, v44, v45
	v_cvt_pk_bf16_f32 v51, v46, v47
	v_add_f32_e32 v230, v40, v230
	v_add_f32_e32 v230, v41, v230
	v_add_f32_e32 v230, v42, v230
	v_add_f32_e32 v230, v43, v230
	v_add_f32_e32 v230, v44, v230
	v_add_f32_e32 v230, v45, v230
	v_add_f32_e32 v230, v46, v230
	v_add_f32_e32 v230, v47, v230
	v_add_f32_e32 v167, v167, v230
	s_waitcnt lgkmcnt(0)
	v_mfma_f32_32x32x16_bf16 v[0:15], v[236:239], v[48:51], v[0:15]
	v_mfma_f32_32x32x16_bf16 v[16:31], a[0:3], v[48:51], v[16:31]
	s_branch .Latt_e_nors_join
.Latt_e_nors_fast:
	v_exp_f32_e32 v48, v48
	v_exp_f32_e32 v49, v49
	v_exp_f32_e32 v50, v50
	v_exp_f32_e32 v51, v51
	v_exp_f32_e32 v52, v52
	v_exp_f32_e32 v53, v53
	v_exp_f32_e32 v54, v54
	v_exp_f32_e32 v55, v55
	s_waitcnt lgkmcnt(14)
	v_mfma_f32_32x32x16_bf16 v[80:95], v[64:67], v[112:115], 0
	v_cvt_pk_bf16_f32 v152, v48, v49
	v_cvt_pk_bf16_f32 v153, v50, v51
	v_cvt_pk_bf16_f32 v154, v52, v53
	v_cvt_pk_bf16_f32 v155, v54, v55
	s_waitcnt lgkmcnt(12)
	v_mfma_f32_32x32x16_bf16 v[64:79], v[68:71], v[112:115], 0
	v_add_f32_e32 v230, 0, v48
	v_add_f32_e32 v230, v49, v230
	v_add_f32_e32 v230, v50, v230
	v_add_f32_e32 v230, v51, v230
	v_add_f32_e32 v230, v52, v230
	v_add_f32_e32 v230, v53, v230
	v_add_f32_e32 v230, v54, v230
	v_add_f32_e32 v230, v55, v230
	v_mfma_f32_32x32x16_bf16 v[80:95], v[168:171], v[96:99], v[80:95]
	s_waitcnt lgkmcnt(11)
	v_mfma_f32_32x32x16_bf16 v[64:79], v[172:175], v[96:99], v[64:79]
	ds_read_b128 v[168:171], v165 offset:13440
	ds_read_b128 v[172:175], v165 offset:13472
	ds_read_b128 v[192:195], v165 offset:20096
	ds_read_b128 v[196:199], v165 offset:20128
	v_exp_f32_e32 v56, v56
	v_exp_f32_e32 v57, v57
	v_exp_f32_e32 v58, v58
	v_exp_f32_e32 v59, v59
	s_waitcnt lgkmcnt(14)
	v_mfma_f32_32x32x16_bf16 v[80:95], v[176:179], v[100:103], v[80:95]
	ds_read2_b64 a[0:3], v241 offset0:44 offset1:46
	v_exp_f32_e32 v60, v60
	v_exp_f32_e32 v61, v61
	v_exp_f32_e32 v62, v62
	v_exp_f32_e32 v63, v63
	s_waitcnt lgkmcnt(13)
	v_mfma_f32_32x32x16_bf16 v[64:79], v[184:187], v[100:103], v[64:79]
	v_mfma_f32_32x32x16_bf16 v[80:95], v[180:183], v[104:107], v[80:95]
	v_cvt_pk_bf16_f32 v48, v56, v57
	v_cvt_pk_bf16_f32 v49, v58, v59
	v_cvt_pk_bf16_f32 v50, v60, v61
	v_cvt_pk_bf16_f32 v51, v62, v63
	s_waitcnt lgkmcnt(12)
	v_mfma_f32_32x32x16_bf16 v[64:79], v[188:191], v[104:107], v[64:79]
	s_waitcnt lgkmcnt(10)
	v_mfma_f32_32x32x16_bf16 v[16:31], v[206:209], v[152:155], v[16:31]
	v_add_f32_e32 v230, v56, v230
	v_add_f32_e32 v230, v57, v230
	v_add_f32_e32 v230, v58, v230
	v_add_f32_e32 v230, v59, v230
	v_add_f32_e32 v230, v60, v230
	v_add_f32_e32 v230, v61, v230
	v_add_f32_e32 v230, v62, v230
	v_add_f32_e32 v230, v63, v230
	v_mfma_f32_32x32x16_bf16 v[0:15], v[210:213], v[152:155], v[0:15]
	s_waitcnt lgkmcnt(4)
	v_mfma_f32_32x32x16_bf16 v[80:95], v[168:171], v[108:111], v[80:95]
	v_exp_f32_e32 v32, v32
	v_exp_f32_e32 v33, v33
	v_exp_f32_e32 v34, v34
	v_exp_f32_e32 v35, v35
	v_mfma_f32_32x32x16_bf16 v[16:31], v[214:217], v[48:51], v[16:31]
	v_exp_f32_e32 v36, v36
	v_exp_f32_e32 v37, v37
	v_exp_f32_e32 v38, v38
	v_exp_f32_e32 v39, v39
	v_mfma_f32_32x32x16_bf16 v[0:15], v[218:221], v[48:51], v[0:15]
	v_cvt_pk_bf16_f32 v152, v32, v33
	v_cvt_pk_bf16_f32 v153, v34, v35
	v_cvt_pk_bf16_f32 v154, v36, v37
	v_cvt_pk_bf16_f32 v155, v38, v39
	s_waitcnt lgkmcnt(2)
	v_mfma_f32_32x32x16_bf16 v[64:79], v[192:195], v[108:111], v[64:79]
	v_add_f32_e32 v230, v32, v230
	v_add_f32_e32 v230, v33, v230
	v_add_f32_e32 v230, v34, v230
	v_add_f32_e32 v230, v35, v230
	v_add_f32_e32 v230, v36, v230
	v_add_f32_e32 v230, v37, v230
	v_add_f32_e32 v230, v38, v230
	v_add_f32_e32 v230, v39, v230
	v_mfma_f32_32x32x16_bf16 v[80:95], v[172:175], v[116:119], v[80:95]
	s_waitcnt lgkmcnt(1)
	v_mfma_f32_32x32x16_bf16 v[64:79], v[196:199], v[116:119], v[64:79]
	s_andn2_b64 vcc, exec, s[10:11]
	s_cbranch_vccnz .Latt_wskip_e2
	s_waitcnt vmcnt(2)
	ds_write_b128 v162, v[120:123]
	s_and_saveexec_b64 s[2:3], s[6:7]
	s_cbranch_execz .Latt_wk_e2
	s_waitcnt vmcnt(1)
	ds_write_b128 v164, v[124:127] offset:128

; #define ATT_LOADK(rk, rr, kt_) do { if (MODE == 3 && (kt_) > 1) break; rk = *(const u32x4*)(gkn + (size_t)(kt_) * 64 * 512); rr = *(const u32x4*)(gkr + (size_t)(kt_) * 64 * 32); } while (0)
; #define ATT_WRITEK(rk, rr, buf) do { LAS unsigned char* nb_ = lds + (buf) * KBUF; *(LAS u32x4*)(nb_ + skn) = rk; if (tid < 256) *(LAS u32x4*)(nb_ + skr) = rr; } while (0)
; #define ATT_WRITEV(rv, buf) do { LAS u32x2* p_ = (LAS u32x2*)(ldsv + (buf) * VBUF + svt); u32x2 lo_ = {rv[0], rv[1]}, hi_ = {rv[2], rv[3]}; p_[0] = lo_; p_[1] = hi_; } while (0)
; template <int MODE>
; __device__ __forceinline__ void attn_phase(const Args& a, bool do_ctx, LAS unsigned char* lds, const int wid_s) {
;     ...
;             if (t + 2 < nkt) ATT_WRITEK(kK, kR, 0);
;             ATT_WRITEV(vV, 1);
;             __syncthreads();
;             if (t + 3 < nkt) ATT_LOADK(kK, kR, t + 3);
.Latt_wskip_e2:
	s_waitcnt vmcnt(0)
	ds_write2_b64 v251, v[128:129], v[130:131] offset1:1
	v_exp_f32_e32 v40, v40
	v_exp_f32_e32 v41, v41
	v_exp_f32_e32 v42, v42
	v_exp_f32_e32 v43, v43
	v_mfma_f32_32x32x16_bf16 v[16:31], v[222:225], v[152:155], v[16:31]
	v_exp_f32_e32 v44, v44
	v_exp_f32_e32 v45, v45
	v_exp_f32_e32 v46, v46
	v_exp_f32_e32 v47, v47
	v_mfma_f32_32x32x16_bf16 v[0:15], v[226:229], v[152:155], v[0:15]
	v_cvt_pk_bf16_f32 v48, v40, v41
	v_cvt_pk_bf16_f32 v49, v42, v43
	v_cvt_pk_bf16_f32 v50, v44, v45
	v_cvt_pk_bf16_f32 v51, v46, v47
	v_add_f32_e32 v230, v40, v230
	v_add_f32_e32 v230, v41, v230
	v_add_f32_e32 v230, v42, v230
	v_add_f32_e32 v230, v43, v230
	v_add_f32_e32 v230, v44, v230
	v_add_f32_e32 v230, v45, v230
	v_add_f32_e32 v230, v46, v230
	v_add_f32_e32 v230, v47, v230
	v_add_f32_e32 v167, v167, v230
	s_waitcnt lgkmcnt(0)
	v_mfma_f32_32x32x16_bf16 v[0:15], v[236:239], v[48:51], v[0:15]
	v_mfma_f32_32x32x16_bf16 v[16:31], a[0:3], v[48:51], v[16:31]
.Latt_e_nors_join:
	s_not_b64 s[8:9], s[10:11]
	s_cmp_lt_u32 s12, s25
	s_cselect_b64 s[10:11], -1, 0
	s_cmp_ge_u32 s12, s25
	s_waitcnt lgkmcnt(0)
	s_barrier
	s_cbranch_scc1 .Latt_o_noK
	s_add_u32 s86, s80, 0x10000
	s_addc_u32 s87, s81, 0
	s_add_u32 s88, s82, 0x1000
	s_addc_u32 s89, s83, 0
	global_load_dwordx4 v[120:123], v146, s[86:87]
	global_load_dwordx4 v[124:127], v148, s[88:89]

; #define LAS __attribute__((address_space(3)))
; __device__ __forceinline__ unsigned pk_bf16(float lo, float hi) { unsigned r; asm("v_cvt_pk_bf16_f32 %0, %1, %2" : "=v"(r) : "v"(lo), "v"(hi)); return r; }
; __device__ __forceinline__ float fexp2(float x) { return __builtin_amdgcn_exp2f(x); }
; #define ATT_WRITEK(rk, rr, buf) do { LAS unsigned char* nb_ = lds + (buf) * KBUF; *(LAS u32x4*)(nb_ + skn) = rk; if (tid < 256) *(LAS u32x4*)(nb_ + skr) = rr; } while (0)
; #define ATT_WRITEV(rv, buf) do { LAS u32x2* p_ = (LAS u32x2*)(ldsv + (buf) * VBUF + svt); u32x2 lo_ = {rv[0], rv[1]}, hi_ = {rv[2], rv[3]}; p_[0] = lo_; p_[1] = hi_; } while (0)
; template <int MODE>
; __device__ __forceinline__ void attn_pv(const LAS unsigned char* vb_, f32x16 (&st)[2], f32x16 (&ot)[2], float& mrun, float& lsum, const int ql, const int hf, const int lane) {
;     ...
;     float ps = 0.f;
; #pragma unroll
;     for (int kb = 0; kb < 2; ++kb)
; #pragma unroll
;         for (int i = 0; i < 16; ++i) { const float p = fexp2(st[kb][i] - mrun); st[kb][i] = p; ps += p; }
;     lsum += ps;
;     } else lsum += st[0][0];
; #pragma unroll
;     for (int kb = 0; kb < 2; ++kb)
; #pragma unroll
;         for (int sI = 0; sI < 2; ++sI) {
;             u32x4 pw = {pk_bf16(st[kb][8 * sI + 0], st[kb][8 * sI + 1]), pk_bf16(st[kb][8 * sI + 2], st[kb][8 * sI + 3]),
;                         pk_bf16(st[kb][8 * sI + 4], st[kb][8 * sI + 5]), pk_bf16(st[kb][8 * sI + 6], st[kb][8 * sI + 7])};
;             const bf16x8 pf = __builtin_bit_cast(bf16x8, pw);
; #pragma unroll
;             for (int db = 0; db < 2; ++db) {
;                 const LAS unsigned char* vp = vb_ + (db * 32 + ql) * VROW + (kb * 32 + 16 * sI + 4 * hf) * 2;
;                 const u32x2 v0 = *(const LAS u32x2*)vp, v1 = *(const LAS u32x2*)(vp + 16);
;                 u32x4 vw = {v0[0], v0[1], v1[0], v1[1]};
;                 ot[db] = att_mma<MODE>(__builtin_bit_cast(bf16x8, vw), pf, ot[db]);
;             }
;         }
; }
; template <int MODE>
; __device__ __forceinline__ void attn_phase(const Args& a, bool do_ctx, LAS unsigned char* lds, const int wid_s) {
;     ...
;             if (t + 3 < nkt) ATT_WRITEK(kK, kR, 1);
;             if (t + 2 < nkt) ATT_WRITEV(vV, 0);
.Latt_o_nors:
	s_cmp_lg_u32 s90, 0
	s_cbranch_scc1 .Latt_o_nors_fast
	v_sub_f32_e32 v80, v80, v143
	v_sub_f32_e32 v81, v81, v143
	v_sub_f32_e32 v82, v82, v143
	v_sub_f32_e32 v83, v83, v143
	v_sub_f32_e32 v84, v84, v143
	v_sub_f32_e32 v85, v85, v143
	v_sub_f32_e32 v86, v86, v143
	v_sub_f32_e32 v87, v87, v143
	v_exp_f32_e32 v80, v80
	v_exp_f32_e32 v81, v81
	v_exp_f32_e32 v82, v82
	v_exp_f32_e32 v83, v83
	v_exp_f32_e32 v84, v84
	v_exp_f32_e32 v85, v85
	v_exp_f32_e32 v86, v86
	v_exp_f32_e32 v87, v87
	s_waitcnt lgkmcnt(14)
	v_mfma_f32_32x32x16_bf16 v[48:63], v[32:35], v[112:115], 0
	v_cvt_pk_bf16_f32 v168, v80, v81
	v_cvt_pk_bf16_f32 v169, v82, v83
	v_cvt_pk_bf16_f32 v170, v84, v85
	v_cvt_pk_bf16_f32 v171, v86, v87
	s_waitcnt lgkmcnt(12)
	v_mfma_f32_32x32x16_bf16 v[32:47], v[36:39], v[112:115], 0
	v_add_f32_e32 v230, 0, v80
	v_add_f32_e32 v230, v81, v230
	v_add_f32_e32 v230, v82, v230
	v_add_f32_e32 v230, v83, v230
	v_add_f32_e32 v230, v84, v230
	v_add_f32_e32 v230, v85, v230
	v_add_f32_e32 v230, v86, v230
	v_add_f32_e32 v230, v87, v230
	v_mfma_f32_32x32x16_bf16 v[48:63], v[152:155], v[96:99], v[48:63]
	v_sub_f32_e32 v88, v88, v143
	v_sub_f32_e32 v89, v89, v143
	v_sub_f32_e32 v90, v90, v143
	v_sub_f32_e32 v91, v91, v143
	v_sub_f32_e32 v92, v92, v143
	v_sub_f32_e32 v93, v93, v143
	v_sub_f32_e32 v94, v94, v143
	v_sub_f32_e32 v95, v95, v143
	s_waitcnt lgkmcnt(11)
	v_mfma_f32_32x32x16_bf16 v[32:47], v[206:209], v[96:99], v[32:47]
	ds_read_b128 v[152:155], v165 offset:128
	ds_read_b128 v[206:209], v165 offset:160
	ds_read_b128 v[226:229], v165 offset:6784
	ds_read_b128 v[236:239], v165 offset:6816
	v_exp_f32_e32 v88, v88
	v_exp_f32_e32 v89, v89
	v_exp_f32_e32 v90, v90
	v_exp_f32_e32 v91, v91
	s_waitcnt lgkmcnt(14)
	v_mfma_f32_32x32x16_bf16 v[48:63], v[210:213], v[100:103], v[48:63]
	ds_read2_b64 a[0:3], v243 offset0:108 offset1:110
	v_exp_f32_e32 v92, v92
	v_exp_f32_e32 v93, v93
	v_exp_f32_e32 v94, v94
	v_exp_f32_e32 v95, v95
	s_waitcnt lgkmcnt(13)
	v_mfma_f32_32x32x16_bf16 v[32:47], v[218:221], v[100:103], v[32:47]
	v_mfma_f32_32x32x16_bf16 v[48:63], v[214:217], v[104:107], v[48:63]
	v_cvt_pk_bf16_f32 v80, v88, v89
	v_cvt_pk_bf16_f32 v81, v90, v91
	v_cvt_pk_bf16_f32 v82, v92, v93
	v_cvt_pk_bf16_f32 v83, v94, v95
	s_waitcnt lgkmcnt(12)
	v_mfma_f32_32x32x16_bf16 v[32:47], v[222:225], v[104:107], v[32:47]
	s_waitcnt lgkmcnt(10)
	v_mfma_f32_32x32x16_bf16 v[0:15], v[176:179], v[168:171], v[0:15]
	v_add_f32_e32 v230, v88, v230
	v_add_f32_e32 v230, v89, v230
	v_add_f32_e32 v230, v90, v230
	v_add_f32_e32 v230, v91, v230
	v_add_f32_e32 v230, v92, v230
	v_add_f32_e32 v230, v93, v230
	v_add_f32_e32 v230, v94, v230
	v_add_f32_e32 v230, v95, v230
	v_mfma_f32_32x32x16_bf16 v[16:31], v[180:183], v[168:171], v[16:31]
	v_sub_f32_e32 v64, v64, v143
	v_sub_f32_e32 v65, v65, v143
	v_sub_f32_e32 v66, v66, v143
	v_sub_f32_e32 v67, v67, v143
	v_sub_f32_e32 v68, v68, v143
	v_sub_f32_e32 v69, v69, v143
	v_sub_f32_e32 v70, v70, v143
	v_sub_f32_e32 v71, v71, v143
	s_waitcnt lgkmcnt(4)
	v_mfma_f32_32x32x16_bf16 v[48:63], v[152:155], v[108:111], v[48:63]
	v_exp_f32_e32 v64, v64
	v_exp_f32_e32 v65, v65
	v_exp_f32_e32 v66, v66
	v_exp_f32_e32 v67, v67
	v_mfma_f32_32x32x16_bf16 v[0:15], v[184:187], v[80:83], v[0:15]
	v_exp_f32_e32 v68, v68
	v_exp_f32_e32 v69, v69
	v_exp_f32_e32 v70, v70
	v_exp_f32_e32 v71, v71
	v_mfma_f32_32x32x16_bf16 v[16:31], v[188:191], v[80:83], v[16:31]
	v_cvt_pk_bf16_f32 v168, v64, v65
	v_cvt_pk_bf16_f32 v169, v66, v67
	v_cvt_pk_bf16_f32 v170, v68, v69
	v_cvt_pk_bf16_f32 v171, v70, v71
	s_waitcnt lgkmcnt(2)
	v_mfma_f32_32x32x16_bf16 v[32:47], v[226:229], v[108:111], v[32:47]
	v_add_f32_e32 v230, v64, v230
	v_add_f32_e32 v230, v65, v230
	v_add_f32_e32 v230, v66, v230
	v_add_f32_e32 v230, v67, v230
	v_add_f32_e32 v230, v68, v230
	v_add_f32_e32 v230, v69, v230
	v_add_f32_e32 v230, v70, v230
	v_add_f32_e32 v230, v71, v230
	v_mfma_f32_32x32x16_bf16 v[48:63], v[206:209], v[116:119], v[48:63]
	v_sub_f32_e32 v72, v72, v143
	v_sub_f32_e32 v73, v73, v143
	v_sub_f32_e32 v74, v74, v143
	v_sub_f32_e32 v75, v75, v143
	v_sub_f32_e32 v76, v76, v143
	v_sub_f32_e32 v77, v77, v143
	v_sub_f32_e32 v78, v78, v143
	v_sub_f32_e32 v79, v79, v143
	s_waitcnt lgkmcnt(1)
	v_mfma_f32_32x32x16_bf16 v[32:47], v[236:239], v[116:119], v[32:47]
	s_andn2_b64 vcc, exec, s[10:11]
	s_cbranch_vccnz .Latt_wskip_o1
	s_waitcnt vmcnt(1)
	ds_write_b128 v162, v[120:123] offset:13312
	s_and_saveexec_b64 s[2:3], s[6:7]
	s_cbranch_execz .Latt_wk_o1
	s_waitcnt vmcnt(0)
	ds_write_b128 v164, v[124:127] offset:13440

; #define LAS __attribute__((address_space(3)))
; __device__ __forceinline__ unsigned pk_bf16(float lo, float hi) { unsigned r; asm("v_cvt_pk_bf16_f32 %0, %1, %2" : "=v"(r) : "v"(lo), "v"(hi)); return r; }
; __device__ __forceinline__ float fexp2(float x) { return __builtin_amdgcn_exp2f(x); }
; #define ATT_WRITEK(rk, rr, buf) do { LAS unsigned char* nb_ = lds + (buf) * KBUF; *(LAS u32x4*)(nb_ + skn) = rk; if (tid < 256) *(LAS u32x4*)(nb_ + skr) = rr; } while (0)
; #define ATT_WRITEV(rv, buf) do { LAS u32x2* p_ = (LAS u32x2*)(ldsv + (buf) * VBUF + svt); u32x2 lo_ = {rv[0], rv[1]}, hi_ = {rv[2], rv[3]}; p_[0] = lo_; p_[1] = hi_; } while (0)
; template <int MODE>
; __device__ __forceinline__ void attn_pv(const LAS unsigned char* vb_, f32x16 (&st)[2], f32x16 (&ot)[2], float& mrun, float& lsum, const int ql, const int hf, const int lane) {
;     ...
;     float ps = 0.f;
; #pragma unroll
;     for (int kb = 0; kb < 2; ++kb)
; #pragma unroll
;         for (int i = 0; i < 16; ++i) { const float p = fexp2(st[kb][i] - mrun); st[kb][i] = p; ps += p; }
;     lsum += ps;
;     } else lsum += st[0][0];
; #pragma unroll
;     for (int kb = 0; kb < 2; ++kb)
; #pragma unroll
;         for (int sI = 0; sI < 2; ++sI) {
;             u32x4 pw = {pk_bf16(st[kb][8 * sI + 0], st[kb][8 * sI + 1]), pk_bf16(st[kb][8 * sI + 2], st[kb][8 * sI + 3]),
;                         pk_bf16(st[kb][8 * sI + 4], st[kb][8 * sI + 5]), pk_bf16(st[kb][8 * sI + 6], st[kb][8 * sI + 7])};
;             const bf16x8 pf = __builtin_bit_cast(bf16x8, pw);
; #pragma unroll
;             for (int db = 0; db < 2; ++db) {
;                 const LAS unsigned char* vp = vb_ + (db * 32 + ql) * VROW + (kb * 32 + 16 * sI + 4 * hf) * 2;
;                 const u32x2 v0 = *(const LAS u32x2*)vp, v1 = *(const LAS u32x2*)(vp + 16);
;                 u32x4 vw = {v0[0], v0[1], v1[0], v1[1]};
;                 ot[db] = att_mma<MODE>(__builtin_bit_cast(bf16x8, vw), pf, ot[db]);
;             }
;         }
; }
; template <int MODE>
; __device__ __forceinline__ void attn_phase(const Args& a, bool do_ctx, LAS unsigned char* lds, const int wid_s) {
;     ...
;             if (t + 3 < nkt) ATT_WRITEK(kK, kR, 1);
;             if (t + 2 < nkt) ATT_WRITEV(vV, 0);
.Latt_wskip_o1:
	s_waitcnt vmcnt(0)
	ds_write2_b64 v141, v[128:129], v[130:131] offset1:1
	v_exp_f32_e32 v72, v72
	v_exp_f32_e32 v73, v73
	v_exp_f32_e32 v74, v74
	v_exp_f32_e32 v75, v75
	v_mfma_f32_32x32x16_bf16 v[0:15], v[192:195], v[168:171], v[0:15]
	v_exp_f32_e32 v76, v76
	v_exp_f32_e32 v77, v77
	v_exp_f32_e32 v78, v78
	v_exp_f32_e32 v79, v79
	v_mfma_f32_32x32x16_bf16 v[16:31], v[196:199], v[168:171], v[16:31]
	v_cvt_pk_bf16_f32 v80, v72, v73
	v_cvt_pk_bf16_f32 v81, v74, v75
	v_cvt_pk_bf16_f32 v82, v76, v77
	v_cvt_pk_bf16_f32 v83, v78, v79
	v_add_f32_e32 v230, v72, v230
	v_add_f32_e32 v230, v73, v230
	v_add_f32_e32 v230, v74, v230
	v_add_f32_e32 v230, v75, v230
	v_add_f32_e32 v230, v76, v230
	v_add_f32_e32 v230, v77, v230
	v_add_f32_e32 v230, v78, v230
	v_add_f32_e32 v230, v79, v230
	v_add_f32_e32 v167, v167, v230
	s_waitcnt lgkmcnt(0)
	v_mfma_f32_32x32x16_bf16 v[0:15], v[172:175], v[80:83], v[0:15]
	v_mfma_f32_32x32x16_bf16 v[16:31], a[0:3], v[80:83], v[16:31]
	s_branch .Latt_o_nors_join
.Latt_o_nors_fast:
	v_exp_f32_e32 v80, v80
	v_exp_f32_e32 v81, v81
	v_exp_f32_e32 v82, v82
	v_exp_f32_e32 v83, v83
	v_exp_f32_e32 v84, v84
	v_exp_f32_e32 v85, v85
	v_exp_f32_e32 v86, v86
	v_exp_f32_e32 v87, v87
	s_waitcnt lgkmcnt(14)
	v_mfma_f32_32x32x16_bf16 v[48:63], v[32:35], v[112:115], 0
	v_cvt_pk_bf16_f32 v168, v80, v81
	v_cvt_pk_bf16_f32 v169, v82, v83
	v_cvt_pk_bf16_f32 v170, v84, v85
	v_cvt_pk_bf16_f32 v171, v86, v87
	s_waitcnt lgkmcnt(12)
	v_mfma_f32_32x32x16_bf16 v[32:47], v[36:39], v[112:115], 0
	v_add_f32_e32 v230, 0, v80
	v_add_f32_e32 v230, v81, v230
	v_add_f32_e32 v230, v82, v230
	v_add_f32_e32 v230, v83, v230
	v_add_f32_e32 v230, v84, v230
	v_add_f32_e32 v230, v85, v230
	v_add_f32_e32 v230, v86, v230
	v_add_f32_e32 v230, v87, v230
	v_mfma_f32_32x32x16_bf16 v[48:63], v[152:155], v[96:99], v[48:63]
	s_waitcnt lgkmcnt(11)
	v_mfma_f32_32x32x16_bf16 v[32:47], v[206:209], v[96:99], v[32:47]
	ds_read_b128 v[152:155], v165 offset:128
	ds_read_b128 v[206:209], v165 offset:160
	ds_read_b128 v[226:229], v165 offset:6784
	ds_read_b128 v[236:239], v165 offset:6816
	v_exp_f32_e32 v88, v88
	v_exp_f32_e32 v89, v89
	v_exp_f32_e32 v90, v90
	v_exp_f32_e32 v91, v91
	s_waitcnt lgkmcnt(14)
	v_mfma_f32_32x32x16_bf16 v[48:63], v[210:213], v[100:103], v[48:63]
	ds_read2_b64 a[0:3], v243 offset0:108 offset1:110
	v_exp_f32_e32 v92, v92
	v_exp_f32_e32 v93, v93
	v_exp_f32_e32 v94, v94
	v_exp_f32_e32 v95, v95
	s_waitcnt lgkmcnt(13)
	v_mfma_f32_32x32x16_bf16 v[32:47], v[218:221], v[100:103], v[32:47]
	v_mfma_f32_32x32x16_bf16 v[48:63], v[214:217], v[104:107], v[48:63]
	v_cvt_pk_bf16_f32 v80, v88, v89
	v_cvt_pk_bf16_f32 v81, v90, v91
	v_cvt_pk_bf16_f32 v82, v92, v93
	v_cvt_pk_bf16_f32 v83, v94, v95
	s_waitcnt lgkmcnt(12)
	v_mfma_f32_32x32x16_bf16 v[32:47], v[222:225], v[104:107], v[32:47]
	s_waitcnt lgkmcnt(10)
	v_mfma_f32_32x32x16_bf16 v[0:15], v[176:179], v[168:171], v[0:15]
	v_add_f32_e32 v230, v88, v230
	v_add_f32_e32 v230, v89, v230
	v_add_f32_e32 v230, v90, v230
	v_add_f32_e32 v230, v91, v230
	v_add_f32_e32 v230, v92, v230
	v_add_f32_e32 v230, v93, v230
	v_add_f32_e32 v230, v94, v230
	v_add_f32_e32 v230, v95, v230
	v_mfma_f32_32x32x16_bf16 v[16:31], v[180:183], v[168:171], v[16:31]
	s_waitcnt lgkmcnt(4)
	v_mfma_f32_32x32x16_bf16 v[48:63], v[152:155], v[108:111], v[48:63]
	v_exp_f32_e32 v64, v64
	v_exp_f32_e32 v65, v65
	v_exp_f32_e32 v66, v66
	v_exp_f32_e32 v67, v67
	v_mfma_f32_32x32x16_bf16 v[0:15], v[184:187], v[80:83], v[0:15]
	v_exp_f32_e32 v68, v68
	v_exp_f32_e32 v69, v69
	v_exp_f32_e32 v70, v70
	v_exp_f32_e32 v71, v71
	v_mfma_f32_32x32x16_bf16 v[16:31], v[188:191], v[80:83], v[16:31]
	v_cvt_pk_bf16_f32 v168, v64, v65
	v_cvt_pk_bf16_f32 v169, v66, v67
	v_cvt_pk_bf16_f32 v170, v68, v69
	v_cvt_pk_bf16_f32 v171, v70, v71
	s_waitcnt lgkmcnt(2)
	v_mfma_f32_32x32x16_bf16 v[32:47], v[226:229], v[108:111], v[32:47]
	v_add_f32_e32 v230, v64, v230
	v_add_f32_e32 v230, v65, v230
	v_add_f32_e32 v230, v66, v230
	v_add_f32_e32 v230, v67, v230
	v_add_f32_e32 v230, v68, v230
	v_add_f32_e32 v230, v69, v230
	v_add_f32_e32 v230, v70, v230
	v_add_f32_e32 v230, v71, v230
	v_mfma_f32_32x32x16_bf16 v[48:63], v[206:209], v[116:119], v[48:63]
	s_waitcnt lgkmcnt(1)
	v_mfma_f32_32x32x16_bf16 v[32:47], v[236:239], v[116:119], v[32:47]
	s_andn2_b64 vcc, exec, s[10:11]
	s_cbranch_vccnz .Latt_wskip_o2
	s_waitcnt vmcnt(1)
	ds_write_b128 v162, v[120:123] offset:13312
	s_and_saveexec_b64 s[2:3], s[6:7]
	s_cbranch_execz .Latt_wk_o2
	s_waitcnt vmcnt(0)
	ds_write_b128 v164, v[124:127] offset:13440

; #define LAS __attribute__((address_space(3)))
; __device__ __forceinline__ unsigned pk_bf16(float lo, float hi) { unsigned r; asm("v_cvt_pk_bf16_f32 %0, %1, %2" : "=v"(r) : "v"(lo), "v"(hi)); return r; }
; __device__ __forceinline__ float fexp2(float x) { return __builtin_amdgcn_exp2f(x); }
; #define ATT_WRITEV(rv, buf) do { LAS u32x2* p_ = (LAS u32x2*)(ldsv + (buf) * VBUF + svt); u32x2 lo_ = {rv[0], rv[1]}, hi_ = {rv[2], rv[3]}; p_[0] = lo_; p_[1] = hi_; } while (0)
; template <int MODE>
; __device__ __forceinline__ void attn_pv(const LAS unsigned char* vb_, f32x16 (&st)[2], f32x16 (&ot)[2], float& mrun, float& lsum, const int ql, const int hf, const int lane) {
;     ...
;     float ps = 0.f;
; #pragma unroll
;     for (int kb = 0; kb < 2; ++kb)
; #pragma unroll
;         for (int i = 0; i < 16; ++i) { const float p = fexp2(st[kb][i] - mrun); st[kb][i] = p; ps += p; }
;     lsum += ps;
;     } else lsum += st[0][0];
; #pragma unroll
;     for (int kb = 0; kb < 2; ++kb)
; #pragma unroll
;         for (int sI = 0; sI < 2; ++sI) {
;             u32x4 pw = {pk_bf16(st[kb][8 * sI + 0], st[kb][8 * sI + 1]), pk_bf16(st[kb][8 * sI + 2], st[kb][8 * sI + 3]),
;                         pk_bf16(st[kb][8 * sI + 4], st[kb][8 * sI + 5]), pk_bf16(st[kb][8 * sI + 6], st[kb][8 * sI + 7])};
;             const bf16x8 pf = __builtin_bit_cast(bf16x8, pw);
; #pragma unroll
;             for (int db = 0; db < 2; ++db) {
;                 const LAS unsigned char* vp = vb_ + (db * 32 + ql) * VROW + (kb * 32 + 16 * sI + 4 * hf) * 2;
;                 const u32x2 v0 = *(const LAS u32x2*)vp, v1 = *(const LAS u32x2*)(vp + 16);
;                 u32x4 vw = {v0[0], v0[1], v1[0], v1[1]};
;                 ot[db] = att_mma<MODE>(__builtin_bit_cast(bf16x8, vw), pf, ot[db]);
;             }
;         }
; }
; template <int MODE>
; __device__ __forceinline__ void attn_phase(const Args& a, bool do_ctx, LAS unsigned char* lds, const int wid_s) {
;     ...
;             if (t + 2 < nkt) ATT_WRITEV(vV, 0);
.Latt_wskip_o2:
	s_waitcnt vmcnt(0)
	ds_write2_b64 v141, v[128:129], v[130:131] offset1:1
	v_exp_f32_e32 v72, v72
	v_exp_f32_e32 v73, v73
	v_exp_f32_e32 v74, v74
	v_exp_f32_e32 v75, v75
	v_mfma_f32_32x32x16_bf16 v[0:15], v[192:195], v[168:171], v[0:15]
	v_exp_f32_e32 v76, v76
	v_exp_f32_e32 v77, v77
	v_exp_f32_e32 v78, v78
	v_exp_f32_e32 v79, v79
	v_mfma_f32_32x32x16_bf16 v[16:31], v[196:199], v[168:171], v[16:31]
	v_cvt_pk_bf16_f32 v80, v72, v73
	v_cvt_pk_bf16_f32 v81, v74, v75
	v_cvt_pk_bf16_f32 v82, v76, v77
	v_cvt_pk_bf16_f32 v83, v78, v79
	v_add_f32_e32 v230, v72, v230
	v_add_f32_e32 v230, v73, v230
	v_add_f32_e32 v230, v74, v230
	v_add_f32_e32 v230, v75, v230
	v_add_f32_e32 v230, v76, v230
	v_add_f32_e32 v230, v77, v230
	v_add_f32_e32 v230, v78, v230
	v_add_f32_e32 v230, v79, v230
	v_add_f32_e32 v167, v167, v230
	s_waitcnt lgkmcnt(0)
	v_mfma_f32_32x32x16_bf16 v[0:15], v[172:175], v[80:83], v[0:15]
	v_mfma_f32_32x32x16_bf16 v[16:31], a[0:3], v[80:83], v[16:31]
